# packed-to-scalar split (doc 7.5): the 5 v_pk_add_f32 in the NA cached-key sweep loop split into v_add_f32 pairs, on top of loop-edge + v_mov_b64 stack
# speedup vs baseline: 1.0094x; 1.0094x over previous
.LBB0_697:
	v_fma_f32 v2, v36, s30, -v161
	v_fma_f32 v36, v52, s30, -v161
	v_exp_f32_e32 v187, v36
	v_fma_f32 v36, v37, s30, -v161
	v_exp_f32_e32 v199, v36
	v_fma_f32 v36, v53, s30, -v161
	v_exp_f32_e32 v218, v36
	v_fma_f32 v36, v38, s30, -v161
	v_exp_f32_e32 v219, v36
	v_fma_f32 v36, v54, s30, -v161
	v_exp_f32_e32 v220, v36
	v_fma_f32 v36, v39, s30, -v161
	v_exp_f32_e32 v221, v36
	v_fma_f32 v36, v55, s30, -v161
	v_exp_f32_e32 v222, v36
	v_fma_f32 v36, v40, s30, -v161
	v_exp_f32_e32 v189, v36
	v_fma_f32 v36, v56, s30, -v161
	v_exp_f32_e32 v188, v36
	v_fma_f32 v36, v41, s30, -v161
	v_exp_f32_e32 v191, v36
	v_fma_f32 v36, v57, s30, -v161
	v_exp_f32_e32 v190, v36
	v_fma_f32 v36, v42, s30, -v161
	v_exp_f32_e32 v193, v36
	v_fma_f32 v36, v58, s30, -v161
	v_exp_f32_e32 v192, v36
	v_fma_f32 v36, v43, s30, -v161
	v_exp_f32_e32 v195, v36
	v_fma_f32 v36, v59, s30, -v161
	v_exp_f32_e32 v194, v36
	v_fma_f32 v36, v44, s30, -v161
	v_exp_f32_e32 v59, v36
	v_fma_f32 v36, v60, s30, -v161
	v_exp_f32_e32 v58, v36
	v_fma_f32 v36, v45, s30, -v161
	v_exp_f32_e32 v197, v36
	v_fma_f32 v36, v61, s30, -v161
	v_exp_f32_e32 v196, v36
	v_fma_f32 v36, v46, s30, -v161
	v_exp_f32_e32 v61, v36
	v_fma_f32 v36, v62, s30, -v161
	v_exp_f32_e32 v60, v36
	v_fma_f32 v36, v47, s30, -v161
	v_exp_f32_e32 v213, v36
	v_fma_f32 v36, v63, s30, -v161
	v_exp_f32_e32 v212, v36
	v_fma_f32 v36, v48, s30, -v161
	v_exp_f32_e32 v63, v36
	v_fma_f32 v36, v64, s30, -v161
	v_exp_f32_e32 v62, v36
	v_fma_f32 v36, v49, s30, -v161
	v_exp_f32_e32 v215, v36
	v_fma_f32 v36, v65, s30, -v161
	v_exp_f32_e32 v214, v36
	v_fma_f32 v36, v50, s30, -v161
	v_exp_f32_e32 v65, v36
	v_fma_f32 v36, v66, s30, -v161
	v_exp_f32_e32 v64, v36
	v_fma_f32 v36, v51, s30, -v161
	v_exp_f32_e32 v217, v36
	v_fma_f32 v36, v67, s30, -v161
	v_exp_f32_e32 v2, v2
	v_exp_f32_e32 v216, v36
	v_cvt_pk_bf16_f32 v36, v2, v199
	v_cvt_pk_bf16_f32 v37, v219, v221
	v_cvt_pk_bf16_f32 v38, v189, v191
	v_cvt_pk_bf16_f32 v39, v193, v195
	v_cvt_pk_bf16_f32 v40, v59, v197
	v_cvt_pk_bf16_f32 v41, v61, v213
	v_cvt_pk_bf16_f32 v42, v63, v215
	v_cvt_pk_bf16_f32 v43, v65, v217
	v_cvt_pk_bf16_f32 v44, v187, v218
	v_cvt_pk_bf16_f32 v45, v220, v222
	v_cvt_pk_bf16_f32 v46, v188, v190
	v_cvt_pk_bf16_f32 v47, v192, v194
	v_cvt_pk_bf16_f32 v48, v58, v196
	v_cvt_pk_bf16_f32 v49, v60, v212
	v_cvt_pk_bf16_f32 v50, v62, v214
	v_cvt_pk_bf16_f32 v51, v64, v216
	ds_read_b64_tr_b16 v[52:53], v164
	ds_read_b64_tr_b16 v[54:55], v164 offset:1152
	ds_read_b64_tr_b16 v[56:57], v164 offset:1216
	s_waitcnt lgkmcnt(1)
	v_mfma_f32_32x32x16_bf16 v[20:35], v[52:55], v[36:39], v[20:35]
	ds_read_b64_tr_b16 v[54:55], v164 offset:64
	v_add_f32_e32 v2, 0, v2
	v_add_f32_e32 v2, v199, v2
	v_add_f32_e32 v2, v219, v2
	s_cmp_lt_u32 s0, 13
	s_waitcnt lgkmcnt(0)
	v_mfma_f32_32x32x16_bf16 v[4:19], v[54:57], v[36:39], v[4:19]
	ds_read_b64_tr_b16 v[36:37], v164 offset:2304
	ds_read_b64_tr_b16 v[38:39], v164 offset:3456
	ds_read_b64_tr_b16 v[54:55], v164 offset:3520
	ds_read_b64_tr_b16 v[52:53], v164 offset:2368
	s_waitcnt lgkmcnt(2)
	v_mfma_f32_32x32x16_bf16 v[20:35], v[36:39], v[40:43], v[20:35]
	ds_read_b64_tr_b16 v[36:37], v164 offset:4608
	ds_read_b64_tr_b16 v[38:39], v164 offset:5760
	s_waitcnt lgkmcnt(2)
	v_mfma_f32_32x32x16_bf16 v[4:19], v[52:55], v[40:43], v[4:19]
	v_add_f32_e32 v40, 0, v187
	v_add_f32_e32 v40, v218, v40
	v_add_f32_e32 v52, v220, v40
	ds_read_b64_tr_b16 v[42:43], v164 offset:5824
	ds_read_b64_tr_b16 v[40:41], v164 offset:4672
	s_waitcnt lgkmcnt(2)
	v_mfma_f32_32x32x16_bf16 v[20:35], v[36:39], v[44:47], v[20:35]
	v_add_f32_e32 v37, v221, v2
	v_add_f32_e32 v36, v222, v52
	v_add_f32_e64 v36, v188, v36
	v_add_f32_e64 v37, v189, v37
	v_add_f32_e64 v36, v190, v36
	v_add_f32_e64 v37, v191, v37
	v_add_f32_e32 v52, v192, v36
	v_add_f32_e32 v53, v193, v37
	s_waitcnt lgkmcnt(0)
	v_mfma_f32_32x32x16_bf16 v[4:19], v[40:43], v[44:47], v[4:19]
	v_add_f32_e64 v40, v194, v52
	v_add_f32_e64 v41, v195, v53
	ds_read_b64_tr_b16 v[36:37], v164 offset:6912
	ds_read_b64_tr_b16 v[38:39], v164 offset:8064
	v_add_f32_e64 v40, v58, v40
	v_add_f32_e64 v41, v59, v41
	v_add_f32_e32 v40, v196, v40
	v_add_f32_e32 v41, v197, v41
	v_add_f32_e32 v40, v60, v40
	v_add_f32_e32 v41, v61, v41
	s_waitcnt lgkmcnt(0)
	v_mfma_f32_32x32x16_bf16 v[20:35], v[36:39], v[48:51], v[20:35]
	v_add_f32_e64 v44, v212, v40
	v_add_f32_e64 v45, v213, v41
	ds_read_b64_tr_b16 v[42:43], v164 offset:8128
	ds_read_b64_tr_b16 v[40:41], v164 offset:6976
	v_add_f32_e64 v36, v62, v44
	v_add_f32_e64 v37, v63, v45
	v_add_f32_e32 v36, v214, v36
	v_add_f32_e32 v37, v215, v37
	v_add_f32_e32 v36, v64, v36
	v_add_f32_e32 v37, v65, v37
	s_waitcnt lgkmcnt(0)
	v_mfma_f32_32x32x16_bf16 v[4:19], v[40:43], v[48:51], v[4:19]
	v_add_f32_e64 v36, v216, v36
	v_add_f32_e64 v37, v217, v37
	v_add_f32_e32 v2, v36, v37
	v_add_f32_e32 v157, v157, v2
	s_cbranch_scc0 .LBB0_700
